# ret_out: drop per-item vmcnt(0) that waited for previous item's store acks (explicit counted waits instead)
# baseline (speedup 1.0000x reference)
.LBB0_748:
	s_bfe_u32 s87, s86, 0x30005
	v_cvt_f32_ubyte0_e32 v0, s87
	v_sub_f32_e32 v0, 0xc0a00000, v0
	s_mov_b32 s0, 0xc2fc0000
	v_cmp_gt_f32_e64 s[0:1], s0, v0
	s_ashr_i32 s88, s86, 8
	v_cndmask_b32_e64 v1, 0, v27, s[0:1]
	v_add_f32_e32 v0, v0, v1
	v_exp_f32_e32 v0, v0
	s_and_b64 s[0:1], s[0:1], exec
	s_cselect_b32 s0, 0xffffffc0, 0
	s_ashr_i32 s89, s88, 31
	v_ldexp_f32 v0, v0, s0
	s_lshl_b64 s[0:1], s[88:89], 12
	s_and_b32 s90, s33, 0xf80
	s_or_b32 s88, s0, s90
	v_sub_f32_e32 v10, 1.0, v0
	s_lshl_b32 s2, s87, 7
	v_mov_b32_e32 v1, s1
	v_or_b32_e32 v0, s88, v26
	v_lshl_add_u64 v[4:5], v[30:31], 0, s[2:3]
	v_lshlrev_b64 v[8:9], 10, v[0:1]
	v_lshl_add_u64 v[0:1], v[4:5], 0, v[8:9]
	s_cmp_eq_u32 s91, 1
	s_cbranch_scc1 .Lro2_pfpath
	global_load_dwordx4 v[120:123], v[0:1], off nt
	v_lshl_add_u64 v[6:7], v[32:33], 0, s[2:3]
	s_mov_b32 s89, s1
	v_add_u32_e32 v24, s90, v42
	v_lshl_add_u64 v[40:41], s[0:1], 0, v[24:25]
	v_log_f32_e32 v39, v10
	v_lshl_add_u64 v[0:1], v[6:7], 0, v[8:9]
	global_load_dwordx4 v[124:127], v[0:1], off nt
	v_lshl_add_u64 v[0:1], s[88:89], 0, v[28:29]
	v_lshlrev_b64 v[8:9], 10, v[0:1]
	v_lshl_add_u64 v[0:1], v[4:5], 0, v[8:9]
	global_load_dwordx4 v[128:131], v[0:1], off nt
	v_lshl_add_u64 v[0:1], v[6:7], 0, v[8:9]
	global_load_dwordx4 v[132:135], v[0:1], off nt
	global_load_dwordx4 v[136:139], v[34:35], off nt
	v_lshlrev_b64 v[0:1], 10, v[40:41]
	v_lshl_add_u64 v[0:1], s[94:95], 0, v[0:1]
	v_lshl_add_u64 v[0:1], v[0:1], 0, s[2:3]
	v_lshl_add_u64 v[0:1], v[0:1], 0, v[36:37]
	global_load_dwordx4 v[4:7], v[0:1], off nt
	s_nop 0
	global_load_dwordx4 v[0:3], v[0:1], off offset:64 nt
	s_waitcnt vmcnt(0)
	s_branch .Lro2_join
.Lro2_pfpath:
	v_add_u32_e32 v24, s90, v42
	v_lshl_add_u64 v[40:41], s[0:1], 0, v[24:25]
	v_log_f32_e32 v39, v10
	s_mov_b32 s89, s1
	s_waitcnt vmcnt(4)
	v_mov_b32_e32 v4, v152
	v_mov_b32_e32 v5, v153
	v_mov_b32_e32 v6, v154
	v_mov_b32_e32 v7, v155
	v_mov_b32_e32 v0, v156
	v_mov_b32_e32 v1, v157
	v_mov_b32_e32 v2, v158
	v_mov_b32_e32 v3, v159
.Lro2_join:
	s_barrier
	s_waitcnt vmcnt(6)
	ds_write_b128 v78, v[120:123]
	s_waitcnt vmcnt(5)
	ds_write_b128 v78, v[124:127] offset:18432
	s_waitcnt vmcnt(4)
	ds_write_b128 v79, v[128:131]
	s_waitcnt vmcnt(3)
	ds_write_b128 v79, v[132:135] offset:18432
	s_waitcnt vmcnt(2)
	ds_write_b128 v80, v[136:139] offset:36864
	s_waitcnt lgkmcnt(0)
	s_barrier
	ds_read_b128 v[8:11], v81
	ds_read_b128 v[12:15], v81 offset:64
	s_waitcnt lgkmcnt(1)
	v_mfma_f32_16x16x32_bf16 v[8:11], v[8:11], v[4:7], 0
	s_waitcnt lgkmcnt(0)
	v_mfma_f32_16x16x32_bf16 v[8:11], v[12:15], v[0:3], v[8:11]
	v_lshlrev_b64 v[150:151], 10, v[40:41]
	v_lshl_add_u64 v[150:151], v[150:151], 0, s[96:97]
	v_mov_b32_e32 v148, v38
	v_mov_b32_e32 v149, 0
	v_lshl_add_u64 v[150:151], v[150:151], 0, s[2:3]
	v_lshl_add_u64 v[150:151], v[150:151], 0, v[148:149]
	global_load_dwordx2 v[140:141], v[150:151], off nt
	global_load_dwordx2 v[142:143], v[150:151], off offset:32 nt
	global_load_dwordx2 v[144:145], v[150:151], off offset:64 nt
	global_load_dwordx2 v[146:147], v[150:151], off offset:96 nt
	s_mov_b32 s91, 0
	s_cmpk_gt_i32 s86, 0x6ef
	s_cbranch_scc1 .Lro2_nopf
	s_add_i32 s98, s86, 0xf8
	s_bfe_u32 s32, s98, 0x30005
	s_lshl_b32 s32, s32, 7
	s_ashr_i32 s100, s98, 8
	s_ashr_i32 s101, s100, 31
	s_lshl_b64 s[100:101], s[100:101], 12
	s_add_i32 s93, s33, 0x7c00
	s_and_b32 s93, s93, 0xf80
	s_or_b32 s98, s100, s93
	v_mov_b32_e32 v160, s32
	v_mov_b32_e32 v161, 0
	v_mov_b32_e32 v163, s101
	v_or_b32_e32 v162, s98, v26
	v_lshlrev_b64 v[162:163], 10, v[162:163]
	v_lshl_add_u64 v[164:165], v[30:31], 0, v[160:161]
	v_lshl_add_u64 v[166:167], v[32:33], 0, v[160:161]
	v_lshl_add_u64 v[168:169], v[164:165], 0, v[162:163]
	global_load_dwordx4 v[120:123], v[168:169], off nt
	v_lshl_add_u64 v[168:169], v[166:167], 0, v[162:163]
	global_load_dwordx4 v[124:127], v[168:169], off nt
	v_mov_b32_e32 v162, s98
	v_mov_b32_e32 v163, s101
	v_lshl_add_u64 v[162:163], v[162:163], 0, v[28:29]
	v_lshlrev_b64 v[162:163], 10, v[162:163]
	v_lshl_add_u64 v[168:169], v[164:165], 0, v[162:163]
	global_load_dwordx4 v[128:131], v[168:169], off nt
	v_lshl_add_u64 v[168:169], v[166:167], 0, v[162:163]
	global_load_dwordx4 v[132:135], v[168:169], off nt
	s_mov_b32 s98, 0x1f0000
	s_mov_b32 s99, 0
	v_lshl_add_u64 v[168:169], v[34:35], 0, s[98:99]
	global_load_dwordx4 v[136:139], v[168:169], off nt
	v_add_u32_e32 v170, s93, v42
	v_mov_b32_e32 v171, v25
	v_mov_b32_e32 v172, s100
	v_mov_b32_e32 v173, s101
	v_lshl_add_u64 v[170:171], v[172:173], 0, v[170:171]
	v_lshlrev_b64 v[170:171], 10, v[170:171]
	v_lshl_add_u64 v[170:171], s[94:95], 0, v[170:171]
	v_lshl_add_u64 v[170:171], v[170:171], 0, v[160:161]
	v_lshl_add_u64 v[170:171], v[170:171], 0, v[36:37]
	global_load_dwordx4 v[152:155], v[170:171], off nt
	global_load_dwordx4 v[156:159], v[170:171], off offset:64 nt
	s_mov_b32 s91, 1
